# grid barrier: agent-scope acquire (buffer_inv sc1) issued at arrival so its latency overlaps the arrival/poll chain; no cached loads happen between arrival and release
# speedup vs baseline: 1.0116x; 1.0116x over previous
; __device__ __forceinline__ unsigned xb_ld(unsigned* p)              { return __hip_atomic_load(p, __ATOMIC_RELAXED, __HIP_MEMORY_SCOPE_AGENT); }
; __device__ __forceinline__ unsigned xb_add(unsigned* p, unsigned v) { return __hip_atomic_fetch_add(p, v, __ATOMIC_RELAXED, __HIP_MEMORY_SCOPE_AGENT); }
; #define XB_SPIN(cond, bar) do { unsigned _sp = 0; while (cond) { __builtin_amdgcn_s_sleep(1); \
;     if ((++_sp & 255u) == 0u) { if (xb_ld(&(bar)[XB_TMO])) break; if (_sp > XB_SPIN_CAP) { atomicAdd(&(bar)[XB_TMO], 1u); break; } } } } while (0)
; __device__ __forceinline__ void xcd_barrier(const XcdBarrier& b) {
;     ...
;         const unsigned old = xb_add(&bar[XB_XSUB(b.x)], 1u);
;         const unsigned gen = old / nloc;
;         if (old + 1u == (gen + 1u) * nloc) {
;             __builtin_amdgcn_fence(__ATOMIC_RELEASE, "agent");
;             asm volatile("s_waitcnt vmcnt(0)" ::: "memory");
;             const unsigned og = xb_add(&bar[XB_TOP], 1u);
;             const unsigned tg = og / nx;
;             if (og + 1u == (tg + 1u) * nx) xb_add(&bar[XB_TOPGEN], 1u);
;             else XB_SPIN(xb_ld(&bar[XB_TOPGEN]) == tg, bar);
;             __builtin_amdgcn_fence(__ATOMIC_ACQUIRE, "agent");
;             xb_add(&bar[XB_XGEN(b.x)], 1u);
;             asm volatile("s_waitcnt vmcnt(0)" ::: "memory");
;         } else {
;             XB_SPIN(xb_ld(&bar[XB_XGEN(b.x)]) == gen, bar);
;             __builtin_amdgcn_fence(__ATOMIC_ACQUIRE, "agent");
.LBB0_46:
	s_or_b64 exec, exec, s[38:39]
	v_cvt_f32_u32_e32 v4, v2
	s_waitcnt vmcnt(0)
	buffer_inv sc1
	v_readfirstlane_b32 s29, v3
	v_sub_u32_e32 v3, 0, v2
	v_rcp_iflag_f32_e32 v4, v4
	v_add_u32_e32 v5, s29, v1
	v_mul_f32_e32 v4, 0x4f7ffffe, v4
	v_cvt_u32_f32_e32 v4, v4
	v_mul_lo_u32 v1, v3, v4
	v_mul_hi_u32 v1, v4, v1
	v_add_u32_e32 v1, v4, v1
	v_mul_hi_u32 v1, v5, v1
	v_mul_lo_u32 v3, v1, v2
	v_sub_u32_e32 v3, v5, v3
	v_add_u32_e32 v4, 1, v1
	v_cmp_ge_u32_e32 vcc, v3, v2
	s_nop 1
	v_cndmask_b32_e32 v1, v1, v4, vcc
	v_sub_u32_e32 v4, v3, v2
	v_cndmask_b32_e32 v3, v3, v4, vcc
	v_add_u32_e32 v4, 1, v1
	v_cmp_ge_u32_e32 vcc, v3, v2
	v_add_u32_e32 v3, 1, v5
	s_nop 0
	v_cndmask_b32_e32 v1, v1, v4, vcc
	v_mul_lo_u32 v4, v2, v1
	v_add_u32_e32 v2, v4, v2
	v_cmp_ne_u32_e32 vcc, v3, v2
	s_and_saveexec_b64 s[34:35], vcc
	s_xor_b64 s[38:39], exec, s[34:35]
	s_cbranch_execz .LBB0_60
	v_readlane_b32 s34, v252, 42
	v_readlane_b32 s35, v252, 43
	s_waitcnt lgkmcnt(0)
	s_nop 3
	global_load_dword v0, v65, s[34:35] sc1
	s_waitcnt vmcnt(0)
	v_cmp_eq_u32_e32 vcc, v0, v1
	s_and_saveexec_b64 s[42:43], vcc
	s_cbranch_execz .LBB0_59
	s_mov_b32 s29, 1
	s_mov_b64 s[44:45], 0
	s_branch .LBB0_50

; __device__ __forceinline__ unsigned xb_ld(unsigned* p)              { return __hip_atomic_load(p, __ATOMIC_RELAXED, __HIP_MEMORY_SCOPE_AGENT); }
; #define XB_SPIN(cond, bar) do { unsigned _sp = 0; while (cond) { __builtin_amdgcn_s_sleep(1); \
;     if ((++_sp & 255u) == 0u) { if (xb_ld(&(bar)[XB_TMO])) break; if (_sp > XB_SPIN_CAP) { atomicAdd(&(bar)[XB_TMO], 1u); break; } } } } while (0)
; __device__ __forceinline__ void xcd_barrier(const XcdBarrier& b) {
;     ...
;             XB_SPIN(xb_ld(&bar[XB_XGEN(b.x)]) == gen, bar);
;             __builtin_amdgcn_fence(__ATOMIC_ACQUIRE, "agent");
;             asm volatile("s_waitcnt vmcnt(0)" ::: "memory");
.LBB0_59:
	s_or_b64 exec, exec, s[42:43]
	s_waitcnt vmcnt(0)
	s_waitcnt vmcnt(0)

; __device__ __forceinline__ unsigned xb_ld(unsigned* p)              { return __hip_atomic_load(p, __ATOMIC_RELAXED, __HIP_MEMORY_SCOPE_AGENT); }
; __device__ __forceinline__ unsigned xb_add(unsigned* p, unsigned v) { return __hip_atomic_fetch_add(p, v, __ATOMIC_RELAXED, __HIP_MEMORY_SCOPE_AGENT); }
; #define XB_SPIN(cond, bar) do { unsigned _sp = 0; while (cond) { __builtin_amdgcn_s_sleep(1); \
;     if ((++_sp & 255u) == 0u) { if (xb_ld(&(bar)[XB_TMO])) break; if (_sp > XB_SPIN_CAP) { atomicAdd(&(bar)[XB_TMO], 1u); break; } } } } while (0)
; __device__ __forceinline__ void xcd_barrier(const XcdBarrier& b) {
;     ...
;             if (og + 1u == (tg + 1u) * nx) xb_add(&bar[XB_TOPGEN], 1u);
;             else XB_SPIN(xb_ld(&bar[XB_TOPGEN]) == tg, bar);
;             __builtin_amdgcn_fence(__ATOMIC_ACQUIRE, "agent");
;             xb_add(&bar[XB_XGEN(b.x)], 1u);
.LBB0_77:
	s_or_b64 exec, exec, s[38:39]
	s_mov_b64 s[38:39], exec
	v_mbcnt_lo_u32_b32 v0, s38, 0
	v_mbcnt_hi_u32_b32 v0, s39, v0
	v_cmp_eq_u32_e32 vcc, 0, v0
	s_waitcnt vmcnt(0)
	s_and_saveexec_b64 s[42:43], vcc
	s_cbranch_execz .LBB0_79
	s_bcnt1_i32_b64 s29, s[38:39]
	v_readlane_b32 s34, v252, 38
	v_mov_b32_e32 v0, s29
	v_readlane_b32 s35, v252, 39
	s_nop 4
	global_atomic_add v65, v0, s[34:35]

; __device__ __forceinline__ unsigned xb_ld(unsigned* p)              { return __hip_atomic_load(p, __ATOMIC_RELAXED, __HIP_MEMORY_SCOPE_AGENT); }
; __device__ __forceinline__ unsigned xb_add(unsigned* p, unsigned v) { return __hip_atomic_fetch_add(p, v, __ATOMIC_RELAXED, __HIP_MEMORY_SCOPE_AGENT); }
; #define XB_SPIN(cond, bar) do { unsigned _sp = 0; while (cond) { __builtin_amdgcn_s_sleep(1); \
;     if ((++_sp & 255u) == 0u) { if (xb_ld(&(bar)[XB_TMO])) break; if (_sp > XB_SPIN_CAP) { atomicAdd(&(bar)[XB_TMO], 1u); break; } } } } while (0)
; __device__ __forceinline__ void xcd_barrier(const XcdBarrier& b) {
;     ...
;         const unsigned old = xb_add(&bar[XB_XSUB(b.x)], 1u);
;         const unsigned gen = old / nloc;
;         if (old + 1u == (gen + 1u) * nloc) {
;             __builtin_amdgcn_fence(__ATOMIC_RELEASE, "agent");
;             asm volatile("s_waitcnt vmcnt(0)" ::: "memory");
;             const unsigned og = xb_add(&bar[XB_TOP], 1u);
;             const unsigned tg = og / nx;
;             if (og + 1u == (tg + 1u) * nx) xb_add(&bar[XB_TOPGEN], 1u);
;             else XB_SPIN(xb_ld(&bar[XB_TOPGEN]) == tg, bar);
;             __builtin_amdgcn_fence(__ATOMIC_ACQUIRE, "agent");
;             xb_add(&bar[XB_XGEN(b.x)], 1u);
;             asm volatile("s_waitcnt vmcnt(0)" ::: "memory");
;         } else {
;             XB_SPIN(xb_ld(&bar[XB_XGEN(b.x)]) == gen, bar);
;             __builtin_amdgcn_fence(__ATOMIC_ACQUIRE, "agent");
.LBB0_1396:
	s_or_b64 exec, exec, s[40:41]
	v_cvt_f32_u32_e32 v4, v2
	s_waitcnt vmcnt(0)
	buffer_inv sc1
	v_readfirstlane_b32 s29, v3
	v_sub_u32_e32 v3, 0, v2
	v_rcp_iflag_f32_e32 v4, v4
	v_add_u32_e32 v5, s29, v1
	v_mul_f32_e32 v4, 0x4f7ffffe, v4
	v_cvt_u32_f32_e32 v4, v4
	v_mul_lo_u32 v1, v3, v4
	v_mul_hi_u32 v1, v4, v1
	v_add_u32_e32 v1, v4, v1
	v_mul_hi_u32 v1, v5, v1
	v_mul_lo_u32 v3, v1, v2
	v_sub_u32_e32 v3, v5, v3
	v_add_u32_e32 v4, 1, v1
	v_cmp_ge_u32_e32 vcc, v3, v2
	s_nop 1
	v_cndmask_b32_e32 v1, v1, v4, vcc
	v_sub_u32_e32 v4, v3, v2
	v_cndmask_b32_e32 v3, v3, v4, vcc
	v_add_u32_e32 v4, 1, v1
	v_cmp_ge_u32_e32 vcc, v3, v2
	v_add_u32_e32 v3, 1, v5
	s_nop 0
	v_cndmask_b32_e32 v1, v1, v4, vcc
	v_mul_lo_u32 v4, v2, v1
	v_add_u32_e32 v2, v4, v2
	v_cmp_ne_u32_e32 vcc, v3, v2
	s_and_saveexec_b64 s[34:35], vcc
	s_xor_b64 s[40:41], exec, s[34:35]
	s_cbranch_execz .LBB0_1410
	v_readlane_b32 s34, v252, 42
	v_readlane_b32 s35, v252, 43
	s_waitcnt lgkmcnt(0)
	s_nop 3
	global_load_dword v0, v65, s[34:35] sc1
	s_waitcnt vmcnt(0)
	v_cmp_eq_u32_e32 vcc, v0, v1
	s_and_saveexec_b64 s[42:43], vcc
	s_cbranch_execz .LBB0_1409
	s_mov_b32 s29, 1
	s_mov_b64 s[44:45], 0
	s_branch .LBB0_1400

; __device__ __forceinline__ unsigned xb_ld(unsigned* p)              { return __hip_atomic_load(p, __ATOMIC_RELAXED, __HIP_MEMORY_SCOPE_AGENT); }
; __device__ __forceinline__ unsigned xb_add(unsigned* p, unsigned v) { return __hip_atomic_fetch_add(p, v, __ATOMIC_RELAXED, __HIP_MEMORY_SCOPE_AGENT); }
; #define XB_SPIN(cond, bar) do { unsigned _sp = 0; while (cond) { __builtin_amdgcn_s_sleep(1); \
;     if ((++_sp & 255u) == 0u) { if (xb_ld(&(bar)[XB_TMO])) break; if (_sp > XB_SPIN_CAP) { atomicAdd(&(bar)[XB_TMO], 1u); break; } } } } while (0)
; __device__ __forceinline__ void xcd_barrier(const XcdBarrier& b) {
;     ...
;             if (og + 1u == (tg + 1u) * nx) xb_add(&bar[XB_TOPGEN], 1u);
;             else XB_SPIN(xb_ld(&bar[XB_TOPGEN]) == tg, bar);
;             __builtin_amdgcn_fence(__ATOMIC_ACQUIRE, "agent");
;             xb_add(&bar[XB_XGEN(b.x)], 1u);
.LBB0_1428:
	s_or_b64 exec, exec, s[40:41]
	s_mov_b64 s[40:41], exec
	v_mbcnt_lo_u32_b32 v0, s40, 0
	v_mbcnt_hi_u32_b32 v0, s41, v0
	v_cmp_eq_u32_e32 vcc, 0, v0
	s_waitcnt vmcnt(0)
	s_and_saveexec_b64 s[42:43], vcc
	s_cbranch_execz .LBB0_1430
	s_bcnt1_i32_b64 s29, s[40:41]
	v_readlane_b32 s34, v252, 38
	v_mov_b32_e32 v0, s29
	v_readlane_b32 s35, v252, 39
	s_nop 4
	global_atomic_add v65, v0, s[34:35]

; __device__ __forceinline__ unsigned xb_ld(unsigned* p)              { return __hip_atomic_load(p, __ATOMIC_RELAXED, __HIP_MEMORY_SCOPE_AGENT); }
; __device__ __forceinline__ unsigned xb_add(unsigned* p, unsigned v) { return __hip_atomic_fetch_add(p, v, __ATOMIC_RELAXED, __HIP_MEMORY_SCOPE_AGENT); }
; #define XB_SPIN(cond, bar) do { unsigned _sp = 0; while (cond) { __builtin_amdgcn_s_sleep(1); \
;     if ((++_sp & 255u) == 0u) { if (xb_ld(&(bar)[XB_TMO])) break; if (_sp > XB_SPIN_CAP) { atomicAdd(&(bar)[XB_TMO], 1u); break; } } } } while (0)
; __device__ __forceinline__ void xcd_barrier(const XcdBarrier& b) {
;     ...
;         const unsigned old = xb_add(&bar[XB_XSUB(b.x)], 1u);
;         const unsigned gen = old / nloc;
;         if (old + 1u == (gen + 1u) * nloc) {
;             __builtin_amdgcn_fence(__ATOMIC_RELEASE, "agent");
;             asm volatile("s_waitcnt vmcnt(0)" ::: "memory");
;             const unsigned og = xb_add(&bar[XB_TOP], 1u);
;             const unsigned tg = og / nx;
;             if (og + 1u == (tg + 1u) * nx) xb_add(&bar[XB_TOPGEN], 1u);
;             else XB_SPIN(xb_ld(&bar[XB_TOPGEN]) == tg, bar);
;             __builtin_amdgcn_fence(__ATOMIC_ACQUIRE, "agent");
;             xb_add(&bar[XB_XGEN(b.x)], 1u);
;             asm volatile("s_waitcnt vmcnt(0)" ::: "memory");
;         } else {
;             XB_SPIN(xb_ld(&bar[XB_XGEN(b.x)]) == gen, bar);
;             __builtin_amdgcn_fence(__ATOMIC_ACQUIRE, "agent");
.LBB0_1451:
	s_or_b64 exec, exec, s[38:39]
	v_cvt_f32_u32_e32 v4, v2
	s_waitcnt vmcnt(0)
	buffer_inv sc1
	v_readfirstlane_b32 s29, v3
	v_sub_u32_e32 v3, 0, v2
	v_rcp_iflag_f32_e32 v4, v4
	v_add_u32_e32 v5, s29, v1
	v_mul_f32_e32 v4, 0x4f7ffffe, v4
	v_cvt_u32_f32_e32 v4, v4
	v_mul_lo_u32 v1, v3, v4
	v_mul_hi_u32 v1, v4, v1
	v_add_u32_e32 v1, v4, v1
	v_mul_hi_u32 v1, v5, v1
	v_mul_lo_u32 v3, v1, v2
	v_sub_u32_e32 v3, v5, v3
	v_add_u32_e32 v4, 1, v1
	v_cmp_ge_u32_e32 vcc, v3, v2
	s_nop 1
	v_cndmask_b32_e32 v1, v1, v4, vcc
	v_sub_u32_e32 v4, v3, v2
	v_cndmask_b32_e32 v3, v3, v4, vcc
	v_add_u32_e32 v4, 1, v1
	v_cmp_ge_u32_e32 vcc, v3, v2
	v_add_u32_e32 v3, 1, v5
	s_nop 0
	v_cndmask_b32_e32 v1, v1, v4, vcc
	v_mul_lo_u32 v4, v2, v1
	v_add_u32_e32 v2, v4, v2
	v_cmp_ne_u32_e32 vcc, v3, v2
	s_and_saveexec_b64 s[34:35], vcc
	s_xor_b64 s[38:39], exec, s[34:35]
	s_cbranch_execz .LBB0_1465
	v_readlane_b32 s34, v252, 42
	v_readlane_b32 s35, v252, 43
	s_waitcnt lgkmcnt(0)
	s_nop 3
	global_load_dword v0, v65, s[34:35] sc1
	s_waitcnt vmcnt(0)
	v_cmp_eq_u32_e32 vcc, v0, v1
	s_and_saveexec_b64 s[40:41], vcc
	s_cbranch_execz .LBB0_1464
	s_mov_b32 s29, 1
	s_mov_b64 s[42:43], 0
	s_branch .LBB0_1455

; __device__ __forceinline__ unsigned xb_ld(unsigned* p)              { return __hip_atomic_load(p, __ATOMIC_RELAXED, __HIP_MEMORY_SCOPE_AGENT); }
; #define XB_SPIN(cond, bar) do { unsigned _sp = 0; while (cond) { __builtin_amdgcn_s_sleep(1); \
;     if ((++_sp & 255u) == 0u) { if (xb_ld(&(bar)[XB_TMO])) break; if (_sp > XB_SPIN_CAP) { atomicAdd(&(bar)[XB_TMO], 1u); break; } } } } while (0)
; __device__ __forceinline__ void xcd_barrier(const XcdBarrier& b) {
;     ...
;             XB_SPIN(xb_ld(&bar[XB_XGEN(b.x)]) == gen, bar);
;             __builtin_amdgcn_fence(__ATOMIC_ACQUIRE, "agent");
;             asm volatile("s_waitcnt vmcnt(0)" ::: "memory");
.LBB0_1464:
	s_or_b64 exec, exec, s[40:41]
	s_waitcnt vmcnt(0)
	s_waitcnt vmcnt(0)

; __device__ __forceinline__ unsigned xb_ld(unsigned* p)              { return __hip_atomic_load(p, __ATOMIC_RELAXED, __HIP_MEMORY_SCOPE_AGENT); }
; __device__ __forceinline__ unsigned xb_add(unsigned* p, unsigned v) { return __hip_atomic_fetch_add(p, v, __ATOMIC_RELAXED, __HIP_MEMORY_SCOPE_AGENT); }
; #define XB_SPIN(cond, bar) do { unsigned _sp = 0; while (cond) { __builtin_amdgcn_s_sleep(1); \
;     if ((++_sp & 255u) == 0u) { if (xb_ld(&(bar)[XB_TMO])) break; if (_sp > XB_SPIN_CAP) { atomicAdd(&(bar)[XB_TMO], 1u); break; } } } } while (0)
; __device__ __forceinline__ void xcd_barrier(const XcdBarrier& b) {
;     ...
;             if (og + 1u == (tg + 1u) * nx) xb_add(&bar[XB_TOPGEN], 1u);
;             else XB_SPIN(xb_ld(&bar[XB_TOPGEN]) == tg, bar);
;             __builtin_amdgcn_fence(__ATOMIC_ACQUIRE, "agent");
;             xb_add(&bar[XB_XGEN(b.x)], 1u);
.LBB0_1482:
	s_or_b64 exec, exec, s[38:39]
	s_mov_b64 s[38:39], exec
	v_mbcnt_lo_u32_b32 v0, s38, 0
	v_mbcnt_hi_u32_b32 v0, s39, v0
	v_cmp_eq_u32_e32 vcc, 0, v0
	s_waitcnt vmcnt(0)
	s_and_saveexec_b64 s[40:41], vcc
	s_cbranch_execz .LBB0_1484
	s_bcnt1_i32_b64 s29, s[38:39]
	v_readlane_b32 s34, v252, 38
	v_mov_b32_e32 v0, s29
	v_readlane_b32 s35, v252, 39
	s_nop 4
	global_atomic_add v65, v0, s[34:35]

; __device__ __forceinline__ unsigned xb_ld(unsigned* p)              { return __hip_atomic_load(p, __ATOMIC_RELAXED, __HIP_MEMORY_SCOPE_AGENT); }
; __device__ __forceinline__ unsigned xb_add(unsigned* p, unsigned v) { return __hip_atomic_fetch_add(p, v, __ATOMIC_RELAXED, __HIP_MEMORY_SCOPE_AGENT); }
; #define XB_SPIN(cond, bar) do { unsigned _sp = 0; while (cond) { __builtin_amdgcn_s_sleep(1); \
;     if ((++_sp & 255u) == 0u) { if (xb_ld(&(bar)[XB_TMO])) break; if (_sp > XB_SPIN_CAP) { atomicAdd(&(bar)[XB_TMO], 1u); break; } } } } while (0)
; __device__ __forceinline__ void xcd_barrier(const XcdBarrier& b) {
;     ...
;             if (og + 1u == (tg + 1u) * nx) xb_add(&bar[XB_TOPGEN], 1u);
;             else XB_SPIN(xb_ld(&bar[XB_TOPGEN]) == tg, bar);
;             __builtin_amdgcn_fence(__ATOMIC_ACQUIRE, "agent");
;             xb_add(&bar[XB_XGEN(b.x)], 1u);
.LBB0_1930:
	s_or_b64 exec, exec, s[38:39]
	s_mov_b64 s[38:39], exec
	v_mbcnt_lo_u32_b32 v0, s38, 0
	v_mbcnt_hi_u32_b32 v0, s39, v0
	v_cmp_eq_u32_e32 vcc, 0, v0
	s_waitcnt vmcnt(0)
	s_and_saveexec_b64 s[40:41], vcc
	s_cbranch_execnz .LBB0_1931
	s_getpc_b64 s[98:99]
